# plus the layer-0 norm copies (both wave roles) converted to the pipelined norm loop, registers remapped onto phase-unused VGPRs, vmcnt drained at loop exit
# baseline (speedup 1.0000x reference)
; __device__ __forceinline__ unsigned cvt_pk_bf16(float lo, float hi) { unsigned r; asm volatile("v_cvt_pk_bf16_f32 %0, %1, %2" : "=v"(r) : "v"(lo), "v"(hi)); return r; }
; __device__ __forceinline__ void phase_norm_mod(const float* x, const float* mod_shift, const float* mod_scale, bf16_t* H, int) {
;     ...
;     const int gw = blockIdx.x * NWAVES + wave, NGW = gridDim.x * NWAVES;
;     constexpr int NR = 4;
;     for (int m0 = gw; m0 < M; m0 += NR * NGW) {
;         f32x4 v[NR][4];
; #pragma unroll
;         for (int r = 0; r < NR; ++r) { const int m = M - 1 - (m0 + r * NGW < M ? m0 + r * NGW : m0); const f32x4* xr = (const f32x4*)(x + (size_t)m * D) + lane;
; #pragma unroll
;             for (int j = 0; j < 4; ++j) v[r][j] = xr[64 * j]; }
; #pragma unroll
;         for (int r = 0; r < NR; ++r) { const int m = M - 1 - (m0 + r * NGW); if (m >= 0) {
;             const int b = m >> 12; float s = 0.f;
; #pragma unroll
;             for (int j = 0; j < 4; ++j) s += (v[r][j].x * v[r][j].x + v[r][j].y * v[r][j].y) + (v[r][j].z * v[r][j].z + v[r][j].w * v[r][j].w);
;             const float rstd = 1.0f / sqrtf(wave_sum(s) * (1.f / D) + 1e-6f);
;             const f32x4* sh = (const f32x4*)(mod_shift + (size_t)b * 6144) + lane;
;             const f32x4* sc = (const f32x4*)(mod_scale + (size_t)b * 6144) + lane;
;             u32x2* o = (u32x2*)(H + (size_t)m * D) + lane;
; #pragma unroll
;             for (int j = 0; j < 4; ++j) { const f32x4 a = sh[64 * j], c = sc[64 * j]; const f32x4 h = v[r][j] * rstd * (c + 1.0f) + a;
;                 u32x2 w; w.x = cvt_pk_bf16(h.x, h.y); w.y = cvt_pk_bf16(h.z, h.w); o[64 * j] = w; } } }
.LBB0_386:
	s_or_b64 exec, exec, s[0:1]
	v_mov_b32_e32 v1, v180
	v_readlane_b32 s8, v234, 36
	v_ashrrev_i32_e32 v0, 6, v1
	v_readlane_b32 s10, v234, 38
	v_add_u32_e32 v64, s70, v0
	s_mov_b32 s18, 0x10000
	v_readlane_b32 s9, v234, 37
	v_readlane_b32 s11, v234, 39
	v_cmp_gt_i32_e32 vcc, s18, v64
	s_and_saveexec_b64 s[14:15], vcc
	s_cbranch_execz .LBB0_395
	v_mov_b32_e32 v201, 0xf800000
	v_lshrrev_b32_e32 v206, 6, v180
	v_and_b32_e32 v207, 63, v180
	v_readfirstlane_b32 s0, v206
	v_lshlrev_b32_e32 v206, 4, v207
	v_lshlrev_b32_e32 v207, 3, v207
	v_mov_b32_e32 v199, 0x358637bd
	v_mov_b32_e32 v200, 0x260
	s_lshl_b32 s1, s24, 3
	s_add_i32 s0, s0, s1
	s_lshl_b32 s2, s28, 3
	s_mul_i32 s1, s2, 3
	s_mov_b32 s19, s0
	s_add_i32 s26, s0, s2
	s_add_i32 s27, s26, s2
	s_cmp_lt_u32 s0, 0x10000
	s_cbranch_scc0 .LNc_done
	s_cmp_lt_u32 s19, 0x10000
	s_cselect_b32 s3, s19, s0
	s_sub_u32 s3, 0xffff, s3
	s_lshl_b32 s4, s3, 12
	s_add_u32 s6, s68, s4
	s_addc_u32 s7, s69, 0
	s_lshr_b32 s4, s3, 12
	s_mul_i32 s4, s4, 0x6000
	s_add_u32 s20, s88, s4
	s_addc_u32 s21, s89, 0
	s_add_u32 s22, s20, 0x101000
	s_addc_u32 s23, s21, 0
	s_add_u32 s20, s20, 0x100000
	s_addc_u32 s21, s21, 0
	global_load_dwordx4 v[0:3], v206, s[6:7]
	global_load_dwordx4 v[4:7], v206, s[6:7] offset:1024
	global_load_dwordx4 v[8:11], v206, s[6:7] offset:2048
	global_load_dwordx4 v[12:15], v206, s[6:7] offset:3072
	global_load_dwordx4 v[16:19], v206, s[22:23]
	global_load_dwordx4 v[20:23], v206, s[22:23] offset:1024
	global_load_dwordx4 v[24:27], v206, s[22:23] offset:2048
	global_load_dwordx4 v[28:31], v206, s[22:23] offset:3072
	global_load_dwordx4 v[32:35], v206, s[20:21]
	global_load_dwordx4 v[36:39], v206, s[20:21] offset:1024
	global_load_dwordx4 v[40:43], v206, s[20:21] offset:2048
	global_load_dwordx4 v[44:47], v206, s[20:21] offset:3072
	s_cmp_lt_u32 s26, 0x10000
	s_cselect_b32 s3, s26, s0
	s_sub_u32 s3, 0xffff, s3
	s_lshl_b32 s4, s3, 12
	s_add_u32 s6, s68, s4
	s_addc_u32 s7, s69, 0
	s_lshr_b32 s4, s3, 12
	s_mul_i32 s4, s4, 0x6000
	s_add_u32 s20, s88, s4
	s_addc_u32 s21, s89, 0
	s_add_u32 s22, s20, 0x101000
	s_addc_u32 s23, s21, 0
	s_add_u32 s20, s20, 0x100000
	s_addc_u32 s21, s21, 0
	global_load_dwordx4 v[48:51], v206, s[6:7]
	global_load_dwordx4 v[52:55], v206, s[6:7] offset:1024
	global_load_dwordx4 v[56:59], v206, s[6:7] offset:2048
	global_load_dwordx4 v[60:63], v206, s[6:7] offset:3072
	global_load_dwordx4 v[64:67], v206, s[22:23]
	global_load_dwordx4 v[68:71], v206, s[22:23] offset:1024
	global_load_dwordx4 v[72:75], v206, s[22:23] offset:2048
	global_load_dwordx4 v[76:79], v206, s[22:23] offset:3072
	global_load_dwordx4 v[80:83], v206, s[20:21]
	global_load_dwordx4 v[84:87], v206, s[20:21] offset:1024
	global_load_dwordx4 v[88:91], v206, s[20:21] offset:2048
	global_load_dwordx4 v[92:95], v206, s[20:21] offset:3072
	s_cmp_lt_u32 s27, 0x10000
	s_cselect_b32 s3, s27, s0
	s_sub_u32 s3, 0xffff, s3
	s_lshl_b32 s4, s3, 12
	s_add_u32 s6, s68, s4
	s_addc_u32 s7, s69, 0
	s_lshr_b32 s4, s3, 12
	s_mul_i32 s4, s4, 0x6000
	s_add_u32 s20, s88, s4
	s_addc_u32 s21, s89, 0
	s_add_u32 s22, s20, 0x101000
	s_addc_u32 s23, s21, 0
	s_add_u32 s20, s20, 0x100000
	s_addc_u32 s21, s21, 0
	global_load_dwordx4 v[122:125], v206, s[6:7]
	global_load_dwordx4 v[126:129], v206, s[6:7] offset:1024
	global_load_dwordx4 v[130:133], v206, s[6:7] offset:2048
	global_load_dwordx4 v[134:137], v206, s[6:7] offset:3072
	global_load_dwordx4 v[138:141], v206, s[22:23]
	global_load_dwordx4 v[142:145], v206, s[22:23] offset:1024
	global_load_dwordx4 v[146:149], v206, s[22:23] offset:2048
	global_load_dwordx4 v[150:153], v206, s[22:23] offset:3072
	global_load_dwordx4 v[154:157], v206, s[20:21]
	global_load_dwordx4 v[158:161], v206, s[20:21] offset:1024
	global_load_dwordx4 v[162:165], v206, s[20:21] offset:2048
	global_load_dwordx4 v[166:169], v206, s[20:21] offset:3072
.LNc_loop:
	s_cmp_lt_u32 s19, 0x10000
	s_cbranch_scc0 .LNc_done
	s_waitcnt vmcnt(24)
	v_pk_mul_f32 v[202:203], v[0:1], v[0:1]
	v_pk_mul_f32 v[204:205], v[2:3], v[2:3]
	v_pk_fma_f32 v[202:203], v[4:5], v[4:5], v[202:203]
	v_pk_fma_f32 v[204:205], v[6:7], v[6:7], v[204:205]
	v_pk_fma_f32 v[202:203], v[8:9], v[8:9], v[202:203]
	v_pk_fma_f32 v[204:205], v[10:11], v[10:11], v[204:205]
	v_pk_fma_f32 v[202:203], v[12:13], v[12:13], v[202:203]
	v_pk_fma_f32 v[204:205], v[14:15], v[14:15], v[204:205]
	v_pk_add_f32 v[202:203], v[202:203], v[204:205]
	s_sub_u32 s3, 0xffff, s19
	s_lshl_b32 s4, s3, 11
	v_add_f32_e32 v190, v202, v203
	s_add_u32 s16, s88, s4
	s_addc_u32 s17, s89, 0
	s_nop 1
	v_add_f32_dpp v190, v190, v190 quad_perm:[1,0,3,2] row_mask:0xf bank_mask:0xf bound_ctrl:1
	s_nop 1
	v_add_f32_dpp v190, v190, v190 quad_perm:[2,3,0,1] row_mask:0xf bank_mask:0xf bound_ctrl:1
	s_nop 1
	v_add_f32_dpp v190, v190, v190 row_half_mirror row_mask:0xf bank_mask:0xf bound_ctrl:1
	s_nop 1
	v_add_f32_dpp v190, v190, v190 row_mirror row_mask:0xf bank_mask:0xf bound_ctrl:1
	s_add_u32 s16, s16, 0x3c00000
	s_addc_u32 s17, s17, 0
	v_readlane_b32 s4, v190, 0
	v_readlane_b32 s5, v190, 16
	v_readlane_b32 s3, v190, 32
	s_nop 1
	v_mov_b32_e32 v191, s4
	v_add_f32_e32 v191, s5, v191
	v_readlane_b32 s4, v190, 48
	v_add_f32_e32 v191, s3, v191
	s_nop 1
	v_add_f32_e32 v190, s4, v191
	v_fmamk_f32 v190, v190, 0x3a800000, v199
	v_mul_f32_e32 v191, 0x4f800000, v190
	v_cmp_gt_f32_e32 vcc, v201, v190
	s_nop 1
	v_cndmask_b32_e32 v192, v190, v191, vcc
	v_sqrt_f32_e32 v194, v192
	s_nop 0
	v_add_u32_e32 v195, -1, v194
	v_add_u32_e32 v196, 1, v194
	v_fma_f32 v197, -v195, v194, v192
	v_fma_f32 v198, -v196, v194, v192
	v_cmp_ge_f32_e64 s[4:5], 0, v197
	s_nop 1
	v_cndmask_b32_e64 v194, v194, v195, s[4:5]
; __device__ __forceinline__ unsigned cvt_pk_bf16(float lo, float hi) { unsigned r; asm volatile("v_cvt_pk_bf16_f32 %0, %1, %2" : "=v"(r) : "v"(lo), "v"(hi)); return r; }
; __device__ __forceinline__ void phase_norm_mod(const float* x, const float* mod_shift, const float* mod_scale, bf16_t* H, int) {
;     ...
;         for (int r = 0; r < NR; ++r) { const int m = M - 1 - (m0 + r * NGW); if (m >= 0) {
;             const int b = m >> 12; float s = 0.f;
; #pragma unroll
;             for (int j = 0; j < 4; ++j) s += (v[r][j].x * v[r][j].x + v[r][j].y * v[r][j].y) + (v[r][j].z * v[r][j].z + v[r][j].w * v[r][j].w);
;             const float rstd = 1.0f / sqrtf(wave_sum(s) * (1.f / D) + 1e-6f);
;             const f32x4* sh = (const f32x4*)(mod_shift + (size_t)b * 6144) + lane;
;             const f32x4* sc = (const f32x4*)(mod_scale + (size_t)b * 6144) + lane;
;             u32x2* o = (u32x2*)(H + (size_t)m * D) + lane;
; #pragma unroll
;             for (int j = 0; j < 4; ++j) { const f32x4 a = sh[64 * j], c = sc[64 * j]; const f32x4 h = v[r][j] * rstd * (c + 1.0f) + a;
;                 u32x2 w; w.x = cvt_pk_bf16(h.x, h.y); w.y = cvt_pk_bf16(h.z, h.w); o[64 * j] = w; } } }
	v_cmp_lt_f32_e64 s[4:5], 0, v198
	s_nop 1
	v_cndmask_b32_e64 v194, v194, v196, s[4:5]
	v_mul_f32_e32 v195, 0x37800000, v194
	v_cndmask_b32_e32 v194, v194, v195, vcc
	v_cmp_class_f32_e32 vcc, v192, v200
	s_nop 1
	v_cndmask_b32_e32 v192, v194, v192, vcc
	v_div_scale_f32 v194, s[4:5], v192, v192, 1.0
	v_rcp_f32_e32 v195, v194
	v_div_scale_f32 v196, vcc, 1.0, v192, 1.0
	v_fma_f32 v197, -v194, v195, 1.0
	v_fmac_f32_e32 v195, v197, v195
	v_mul_f32_e32 v197, v196, v195
	v_fma_f32 v198, -v194, v197, v196
	v_fmac_f32_e32 v197, v198, v195
	v_fma_f32 v194, -v194, v197, v196
	v_div_fmas_f32 v194, v194, v195, v197
	v_div_fixup_f32 v192, v194, v192, 1.0
	v_pk_mul_f32 v[0:1], v[0:1], v[192:193] op_sel_hi:[1,0]
	v_pk_mul_f32 v[2:3], v[2:3], v[192:193] op_sel_hi:[1,0]
	v_pk_add_f32 v[16:17], v[16:17], 1.0 op_sel_hi:[1,0]
	v_pk_add_f32 v[18:19], v[18:19], 1.0 op_sel_hi:[1,0]
	v_pk_fma_f32 v[0:1], v[16:17], v[0:1], v[32:33]
	v_pk_fma_f32 v[2:3], v[18:19], v[2:3], v[34:35]
	v_cvt_pk_bf16_f32 v182, v0, v1
	v_cvt_pk_bf16_f32 v183, v2, v3
	v_pk_mul_f32 v[4:5], v[4:5], v[192:193] op_sel_hi:[1,0]
	v_pk_mul_f32 v[6:7], v[6:7], v[192:193] op_sel_hi:[1,0]
	v_pk_add_f32 v[20:21], v[20:21], 1.0 op_sel_hi:[1,0]
	v_pk_add_f32 v[22:23], v[22:23], 1.0 op_sel_hi:[1,0]
	v_pk_fma_f32 v[4:5], v[20:21], v[4:5], v[36:37]
	v_pk_fma_f32 v[6:7], v[22:23], v[6:7], v[38:39]
	v_cvt_pk_bf16_f32 v184, v4, v5
	v_cvt_pk_bf16_f32 v185, v6, v7
	v_pk_mul_f32 v[8:9], v[8:9], v[192:193] op_sel_hi:[1,0]
	v_pk_mul_f32 v[10:11], v[10:11], v[192:193] op_sel_hi:[1,0]
	v_pk_add_f32 v[24:25], v[24:25], 1.0 op_sel_hi:[1,0]
	v_pk_add_f32 v[26:27], v[26:27], 1.0 op_sel_hi:[1,0]
	v_pk_fma_f32 v[8:9], v[24:25], v[8:9], v[40:41]
	v_pk_fma_f32 v[10:11], v[26:27], v[10:11], v[42:43]
	v_cvt_pk_bf16_f32 v186, v8, v9
	v_cvt_pk_bf16_f32 v187, v10, v11
	v_pk_mul_f32 v[12:13], v[12:13], v[192:193] op_sel_hi:[1,0]
	v_pk_mul_f32 v[14:15], v[14:15], v[192:193] op_sel_hi:[1,0]
	v_pk_add_f32 v[28:29], v[28:29], 1.0 op_sel_hi:[1,0]
	v_pk_add_f32 v[30:31], v[30:31], 1.0 op_sel_hi:[1,0]
	v_pk_fma_f32 v[12:13], v[28:29], v[12:13], v[44:45]
	v_pk_fma_f32 v[14:15], v[30:31], v[14:15], v[46:47]
	v_cvt_pk_bf16_f32 v188, v12, v13
	v_cvt_pk_bf16_f32 v189, v14, v15
	global_store_dwordx2 v207, v[182:183], s[16:17]
	global_store_dwordx2 v207, v[184:185], s[16:17] offset:512
	global_store_dwordx2 v207, v[186:187], s[16:17] offset:1024
	global_store_dwordx2 v207, v[188:189], s[16:17] offset:1536
	s_add_i32 s19, s19, s1
	s_cmp_lt_u32 s19, 0x10000
	s_cselect_b32 s3, s19, s0
	s_sub_u32 s3, 0xffff, s3
	s_lshl_b32 s4, s3, 12
	s_add_u32 s6, s68, s4
	s_addc_u32 s7, s69, 0
	s_lshr_b32 s4, s3, 12
	s_mul_i32 s4, s4, 0x6000
	s_add_u32 s20, s88, s4
	s_addc_u32 s21, s89, 0
	s_add_u32 s22, s20, 0x101000
	s_addc_u32 s23, s21, 0
	s_add_u32 s20, s20, 0x100000
	s_addc_u32 s21, s21, 0
	global_load_dwordx4 v[0:3], v206, s[6:7]
	global_load_dwordx4 v[4:7], v206, s[6:7] offset:1024
	global_load_dwordx4 v[8:11], v206, s[6:7] offset:2048
	global_load_dwordx4 v[12:15], v206, s[6:7] offset:3072
	global_load_dwordx4 v[16:19], v206, s[22:23]
	global_load_dwordx4 v[20:23], v206, s[22:23] offset:1024
	global_load_dwordx4 v[24:27], v206, s[22:23] offset:2048
	global_load_dwordx4 v[28:31], v206, s[22:23] offset:3072
	global_load_dwordx4 v[32:35], v206, s[20:21]
	global_load_dwordx4 v[36:39], v206, s[20:21] offset:1024
	global_load_dwordx4 v[40:43], v206, s[20:21] offset:2048
	global_load_dwordx4 v[44:47], v206, s[20:21] offset:3072
	s_cmp_lt_u32 s26, 0x10000
	s_cbranch_scc0 .LNc_done
	s_waitcnt vmcnt(24)
	v_pk_mul_f32 v[202:203], v[48:49], v[48:49]
	v_pk_mul_f32 v[204:205], v[50:51], v[50:51]
	v_pk_fma_f32 v[202:203], v[52:53], v[52:53], v[202:203]
	v_pk_fma_f32 v[204:205], v[54:55], v[54:55], v[204:205]
	v_pk_fma_f32 v[202:203], v[56:57], v[56:57], v[202:203]
	v_pk_fma_f32 v[204:205], v[58:59], v[58:59], v[204:205]
	v_pk_fma_f32 v[202:203], v[60:61], v[60:61], v[202:203]
	v_pk_fma_f32 v[204:205], v[62:63], v[62:63], v[204:205]
	v_pk_add_f32 v[202:203], v[202:203], v[204:205]
	s_sub_u32 s3, 0xffff, s26
	s_lshl_b32 s4, s3, 11
	v_add_f32_e32 v190, v202, v203
	s_add_u32 s16, s88, s4
	s_addc_u32 s17, s89, 0
	s_nop 1
	v_add_f32_dpp v190, v190, v190 quad_perm:[1,0,3,2] row_mask:0xf bank_mask:0xf bound_ctrl:1
	s_nop 1
	v_add_f32_dpp v190, v190, v190 quad_perm:[2,3,0,1] row_mask:0xf bank_mask:0xf bound_ctrl:1
	s_nop 1
	v_add_f32_dpp v190, v190, v190 row_half_mirror row_mask:0xf bank_mask:0xf bound_ctrl:1
	s_nop 1
	v_add_f32_dpp v190, v190, v190 row_mirror row_mask:0xf bank_mask:0xf bound_ctrl:1
	s_add_u32 s16, s16, 0x3c00000
	s_addc_u32 s17, s17, 0
	v_readlane_b32 s4, v190, 0
	v_readlane_b32 s5, v190, 16
	v_readlane_b32 s3, v190, 32
	s_nop 1
	v_mov_b32_e32 v191, s4
	v_add_f32_e32 v191, s5, v191
	v_readlane_b32 s4, v190, 48
	v_add_f32_e32 v191, s3, v191
	s_nop 1
	v_add_f32_e32 v190, s4, v191
	v_fmamk_f32 v190, v190, 0x3a800000, v199
	v_mul_f32_e32 v191, 0x4f800000, v190
	v_cmp_gt_f32_e32 vcc, v201, v190
	s_nop 1
	v_cndmask_b32_e32 v192, v190, v191, vcc
	v_sqrt_f32_e32 v194, v192
	s_nop 0
	v_add_u32_e32 v195, -1, v194
	v_add_u32_e32 v196, 1, v194
	v_fma_f32 v197, -v195, v194, v192
	v_fma_f32 v198, -v196, v194, v192
	v_cmp_ge_f32_e64 s[4:5], 0, v197
	s_nop 1
	v_cndmask_b32_e64 v194, v194, v195, s[4:5]
	v_cmp_lt_f32_e64 s[4:5], 0, v198
	s_nop 1
	v_cndmask_b32_e64 v194, v194, v196, s[4:5]
	v_mul_f32_e32 v195, 0x37800000, v194
	v_cndmask_b32_e32 v194, v194, v195, vcc
	v_cmp_class_f32_e32 vcc, v192, v200
	s_nop 1
	v_cndmask_b32_e32 v192, v194, v192, vcc
	v_div_scale_f32 v194, s[4:5], v192, v192, 1.0
	v_rcp_f32_e32 v195, v194
	v_div_scale_f32 v196, vcc, 1.0, v192, 1.0
; __device__ __forceinline__ unsigned cvt_pk_bf16(float lo, float hi) { unsigned r; asm volatile("v_cvt_pk_bf16_f32 %0, %1, %2" : "=v"(r) : "v"(lo), "v"(hi)); return r; }
; __device__ __forceinline__ void phase_norm_mod(const float* x, const float* mod_shift, const float* mod_scale, bf16_t* H, int) {
;     ...
;         for (int r = 0; r < NR; ++r) { const int m = M - 1 - (m0 + r * NGW); if (m >= 0) {
;             const int b = m >> 12; float s = 0.f;
; #pragma unroll
;             for (int j = 0; j < 4; ++j) s += (v[r][j].x * v[r][j].x + v[r][j].y * v[r][j].y) + (v[r][j].z * v[r][j].z + v[r][j].w * v[r][j].w);
;             const float rstd = 1.0f / sqrtf(wave_sum(s) * (1.f / D) + 1e-6f);
;             const f32x4* sh = (const f32x4*)(mod_shift + (size_t)b * 6144) + lane;
;             const f32x4* sc = (const f32x4*)(mod_scale + (size_t)b * 6144) + lane;
;             u32x2* o = (u32x2*)(H + (size_t)m * D) + lane;
; #pragma unroll
;             for (int j = 0; j < 4; ++j) { const f32x4 a = sh[64 * j], c = sc[64 * j]; const f32x4 h = v[r][j] * rstd * (c + 1.0f) + a;
;                 u32x2 w; w.x = cvt_pk_bf16(h.x, h.y); w.y = cvt_pk_bf16(h.z, h.w); o[64 * j] = w; } } }
	v_fma_f32 v197, -v194, v195, 1.0
	v_fmac_f32_e32 v195, v197, v195
	v_mul_f32_e32 v197, v196, v195
	v_fma_f32 v198, -v194, v197, v196
	v_fmac_f32_e32 v197, v198, v195
	v_fma_f32 v194, -v194, v197, v196
	v_div_fmas_f32 v194, v194, v195, v197
	v_div_fixup_f32 v192, v194, v192, 1.0
	v_pk_mul_f32 v[48:49], v[48:49], v[192:193] op_sel_hi:[1,0]
	v_pk_mul_f32 v[50:51], v[50:51], v[192:193] op_sel_hi:[1,0]
	v_pk_add_f32 v[64:65], v[64:65], 1.0 op_sel_hi:[1,0]
	v_pk_add_f32 v[66:67], v[66:67], 1.0 op_sel_hi:[1,0]
	v_pk_fma_f32 v[48:49], v[64:65], v[48:49], v[80:81]
	v_pk_fma_f32 v[50:51], v[66:67], v[50:51], v[82:83]
	v_cvt_pk_bf16_f32 v182, v48, v49
	v_cvt_pk_bf16_f32 v183, v50, v51
	v_pk_mul_f32 v[52:53], v[52:53], v[192:193] op_sel_hi:[1,0]
	v_pk_mul_f32 v[54:55], v[54:55], v[192:193] op_sel_hi:[1,0]
	v_pk_add_f32 v[68:69], v[68:69], 1.0 op_sel_hi:[1,0]
	v_pk_add_f32 v[70:71], v[70:71], 1.0 op_sel_hi:[1,0]
	v_pk_fma_f32 v[52:53], v[68:69], v[52:53], v[84:85]
	v_pk_fma_f32 v[54:55], v[70:71], v[54:55], v[86:87]
	v_cvt_pk_bf16_f32 v184, v52, v53
	v_cvt_pk_bf16_f32 v185, v54, v55
	v_pk_mul_f32 v[56:57], v[56:57], v[192:193] op_sel_hi:[1,0]
	v_pk_mul_f32 v[58:59], v[58:59], v[192:193] op_sel_hi:[1,0]
	v_pk_add_f32 v[72:73], v[72:73], 1.0 op_sel_hi:[1,0]
	v_pk_add_f32 v[74:75], v[74:75], 1.0 op_sel_hi:[1,0]
	v_pk_fma_f32 v[56:57], v[72:73], v[56:57], v[88:89]
	v_pk_fma_f32 v[58:59], v[74:75], v[58:59], v[90:91]
	v_cvt_pk_bf16_f32 v186, v56, v57
	v_cvt_pk_bf16_f32 v187, v58, v59
	v_pk_mul_f32 v[60:61], v[60:61], v[192:193] op_sel_hi:[1,0]
	v_pk_mul_f32 v[62:63], v[62:63], v[192:193] op_sel_hi:[1,0]
	v_pk_add_f32 v[76:77], v[76:77], 1.0 op_sel_hi:[1,0]
	v_pk_add_f32 v[78:79], v[78:79], 1.0 op_sel_hi:[1,0]
	v_pk_fma_f32 v[60:61], v[76:77], v[60:61], v[92:93]
	v_pk_fma_f32 v[62:63], v[78:79], v[62:63], v[94:95]
	v_cvt_pk_bf16_f32 v188, v60, v61
	v_cvt_pk_bf16_f32 v189, v62, v63
	global_store_dwordx2 v207, v[182:183], s[16:17]
	global_store_dwordx2 v207, v[184:185], s[16:17] offset:512
	global_store_dwordx2 v207, v[186:187], s[16:17] offset:1024
	global_store_dwordx2 v207, v[188:189], s[16:17] offset:1536
	s_add_i32 s26, s26, s1
	s_cmp_lt_u32 s26, 0x10000
	s_cselect_b32 s3, s26, s0
	s_sub_u32 s3, 0xffff, s3
	s_lshl_b32 s4, s3, 12
	s_add_u32 s6, s68, s4
	s_addc_u32 s7, s69, 0
	s_lshr_b32 s4, s3, 12
	s_mul_i32 s4, s4, 0x6000
	s_add_u32 s20, s88, s4
	s_addc_u32 s21, s89, 0
	s_add_u32 s22, s20, 0x101000
	s_addc_u32 s23, s21, 0
	s_add_u32 s20, s20, 0x100000
	s_addc_u32 s21, s21, 0
	global_load_dwordx4 v[48:51], v206, s[6:7]
	global_load_dwordx4 v[52:55], v206, s[6:7] offset:1024
	global_load_dwordx4 v[56:59], v206, s[6:7] offset:2048
	global_load_dwordx4 v[60:63], v206, s[6:7] offset:3072
	global_load_dwordx4 v[64:67], v206, s[22:23]
	global_load_dwordx4 v[68:71], v206, s[22:23] offset:1024
	global_load_dwordx4 v[72:75], v206, s[22:23] offset:2048
	global_load_dwordx4 v[76:79], v206, s[22:23] offset:3072
	global_load_dwordx4 v[80:83], v206, s[20:21]
	global_load_dwordx4 v[84:87], v206, s[20:21] offset:1024
	global_load_dwordx4 v[88:91], v206, s[20:21] offset:2048
	global_load_dwordx4 v[92:95], v206, s[20:21] offset:3072
	s_cmp_lt_u32 s27, 0x10000
	s_cbranch_scc0 .LNc_done
	s_waitcnt vmcnt(24)
	v_pk_mul_f32 v[202:203], v[122:123], v[122:123]
	v_pk_mul_f32 v[204:205], v[124:125], v[124:125]
	v_pk_fma_f32 v[202:203], v[126:127], v[126:127], v[202:203]
	v_pk_fma_f32 v[204:205], v[128:129], v[128:129], v[204:205]
	v_pk_fma_f32 v[202:203], v[130:131], v[130:131], v[202:203]
	v_pk_fma_f32 v[204:205], v[132:133], v[132:133], v[204:205]
	v_pk_fma_f32 v[202:203], v[134:135], v[134:135], v[202:203]
	v_pk_fma_f32 v[204:205], v[136:137], v[136:137], v[204:205]
	v_pk_add_f32 v[202:203], v[202:203], v[204:205]
	s_sub_u32 s3, 0xffff, s27
	s_lshl_b32 s4, s3, 11
	v_add_f32_e32 v190, v202, v203
	s_add_u32 s16, s88, s4
	s_addc_u32 s17, s89, 0
	s_nop 1
	v_add_f32_dpp v190, v190, v190 quad_perm:[1,0,3,2] row_mask:0xf bank_mask:0xf bound_ctrl:1
	s_nop 1
	v_add_f32_dpp v190, v190, v190 quad_perm:[2,3,0,1] row_mask:0xf bank_mask:0xf bound_ctrl:1
	s_nop 1
	v_add_f32_dpp v190, v190, v190 row_half_mirror row_mask:0xf bank_mask:0xf bound_ctrl:1
	s_nop 1
	v_add_f32_dpp v190, v190, v190 row_mirror row_mask:0xf bank_mask:0xf bound_ctrl:1
	s_add_u32 s16, s16, 0x3c00000
	s_addc_u32 s17, s17, 0
	v_readlane_b32 s4, v190, 0
	v_readlane_b32 s5, v190, 16
	v_readlane_b32 s3, v190, 32
	s_nop 1
	v_mov_b32_e32 v191, s4
	v_add_f32_e32 v191, s5, v191
	v_readlane_b32 s4, v190, 48
	v_add_f32_e32 v191, s3, v191
	s_nop 1
	v_add_f32_e32 v190, s4, v191
	v_fmamk_f32 v190, v190, 0x3a800000, v199
	v_mul_f32_e32 v191, 0x4f800000, v190
	v_cmp_gt_f32_e32 vcc, v201, v190
	s_nop 1
	v_cndmask_b32_e32 v192, v190, v191, vcc
	v_sqrt_f32_e32 v194, v192
	s_nop 0
	v_add_u32_e32 v195, -1, v194
	v_add_u32_e32 v196, 1, v194
	v_fma_f32 v197, -v195, v194, v192
	v_fma_f32 v198, -v196, v194, v192
	v_cmp_ge_f32_e64 s[4:5], 0, v197
	s_nop 1
	v_cndmask_b32_e64 v194, v194, v195, s[4:5]
	v_cmp_lt_f32_e64 s[4:5], 0, v198
	s_nop 1
	v_cndmask_b32_e64 v194, v194, v196, s[4:5]
	v_mul_f32_e32 v195, 0x37800000, v194
	v_cndmask_b32_e32 v194, v194, v195, vcc
	v_cmp_class_f32_e32 vcc, v192, v200
	s_nop 1
	v_cndmask_b32_e32 v192, v194, v192, vcc
	v_div_scale_f32 v194, s[4:5], v192, v192, 1.0
	v_rcp_f32_e32 v195, v194
	v_div_scale_f32 v196, vcc, 1.0, v192, 1.0
	v_fma_f32 v197, -v194, v195, 1.0
	v_fmac_f32_e32 v195, v197, v195
	v_mul_f32_e32 v197, v196, v195
	v_fma_f32 v198, -v194, v197, v196
	v_fmac_f32_e32 v197, v198, v195
	v_fma_f32 v194, -v194, v197, v196
	v_div_fmas_f32 v194, v194, v195, v197
	v_div_fixup_f32 v192, v194, v192, 1.0
; __device__ __forceinline__ unsigned cvt_pk_bf16(float lo, float hi) { unsigned r; asm volatile("v_cvt_pk_bf16_f32 %0, %1, %2" : "=v"(r) : "v"(lo), "v"(hi)); return r; }
; __device__ __forceinline__ void phase_norm_mod(const float* x, const float* mod_shift, const float* mod_scale, bf16_t* H, int) {
;     ...
;     for (int m0 = gw; m0 < M; m0 += NR * NGW) {
;         f32x4 v[NR][4];
; #pragma unroll
;         for (int r = 0; r < NR; ++r) { const int m = M - 1 - (m0 + r * NGW < M ? m0 + r * NGW : m0); const f32x4* xr = (const f32x4*)(x + (size_t)m * D) + lane;
; #pragma unroll
;             for (int j = 0; j < 4; ++j) v[r][j] = xr[64 * j]; }
; #pragma unroll
;         for (int r = 0; r < NR; ++r) { const int m = M - 1 - (m0 + r * NGW); if (m >= 0) {
;             const int b = m >> 12; float s = 0.f;
; #pragma unroll
;             for (int j = 0; j < 4; ++j) s += (v[r][j].x * v[r][j].x + v[r][j].y * v[r][j].y) + (v[r][j].z * v[r][j].z + v[r][j].w * v[r][j].w);
;             const float rstd = 1.0f / sqrtf(wave_sum(s) * (1.f / D) + 1e-6f);
;             const f32x4* sh = (const f32x4*)(mod_shift + (size_t)b * 6144) + lane;
;             const f32x4* sc = (const f32x4*)(mod_scale + (size_t)b * 6144) + lane;
;             u32x2* o = (u32x2*)(H + (size_t)m * D) + lane;
; #pragma unroll
;             for (int j = 0; j < 4; ++j) { const f32x4 a = sh[64 * j], c = sc[64 * j]; const f32x4 h = v[r][j] * rstd * (c + 1.0f) + a;
;                 u32x2 w; w.x = cvt_pk_bf16(h.x, h.y); w.y = cvt_pk_bf16(h.z, h.w); o[64 * j] = w; } } }
	v_pk_mul_f32 v[122:123], v[122:123], v[192:193] op_sel_hi:[1,0]
	v_pk_mul_f32 v[124:125], v[124:125], v[192:193] op_sel_hi:[1,0]
	v_pk_add_f32 v[138:139], v[138:139], 1.0 op_sel_hi:[1,0]
	v_pk_add_f32 v[140:141], v[140:141], 1.0 op_sel_hi:[1,0]
	v_pk_fma_f32 v[122:123], v[138:139], v[122:123], v[154:155]
	v_pk_fma_f32 v[124:125], v[140:141], v[124:125], v[156:157]
	v_cvt_pk_bf16_f32 v182, v122, v123
	v_cvt_pk_bf16_f32 v183, v124, v125
	v_pk_mul_f32 v[126:127], v[126:127], v[192:193] op_sel_hi:[1,0]
	v_pk_mul_f32 v[128:129], v[128:129], v[192:193] op_sel_hi:[1,0]
	v_pk_add_f32 v[142:143], v[142:143], 1.0 op_sel_hi:[1,0]
	v_pk_add_f32 v[144:145], v[144:145], 1.0 op_sel_hi:[1,0]
	v_pk_fma_f32 v[126:127], v[142:143], v[126:127], v[158:159]
	v_pk_fma_f32 v[128:129], v[144:145], v[128:129], v[160:161]
	v_cvt_pk_bf16_f32 v184, v126, v127
	v_cvt_pk_bf16_f32 v185, v128, v129
	v_pk_mul_f32 v[130:131], v[130:131], v[192:193] op_sel_hi:[1,0]
	v_pk_mul_f32 v[132:133], v[132:133], v[192:193] op_sel_hi:[1,0]
	v_pk_add_f32 v[146:147], v[146:147], 1.0 op_sel_hi:[1,0]
	v_pk_add_f32 v[148:149], v[148:149], 1.0 op_sel_hi:[1,0]
	v_pk_fma_f32 v[130:131], v[146:147], v[130:131], v[162:163]
	v_pk_fma_f32 v[132:133], v[148:149], v[132:133], v[164:165]
	v_cvt_pk_bf16_f32 v186, v130, v131
	v_cvt_pk_bf16_f32 v187, v132, v133
	v_pk_mul_f32 v[134:135], v[134:135], v[192:193] op_sel_hi:[1,0]
	v_pk_mul_f32 v[136:137], v[136:137], v[192:193] op_sel_hi:[1,0]
	v_pk_add_f32 v[150:151], v[150:151], 1.0 op_sel_hi:[1,0]
	v_pk_add_f32 v[152:153], v[152:153], 1.0 op_sel_hi:[1,0]
	v_pk_fma_f32 v[134:135], v[150:151], v[134:135], v[166:167]
	v_pk_fma_f32 v[136:137], v[152:153], v[136:137], v[168:169]
	v_cvt_pk_bf16_f32 v188, v134, v135
	v_cvt_pk_bf16_f32 v189, v136, v137
	global_store_dwordx2 v207, v[182:183], s[16:17]
	global_store_dwordx2 v207, v[184:185], s[16:17] offset:512
	global_store_dwordx2 v207, v[186:187], s[16:17] offset:1024
	global_store_dwordx2 v207, v[188:189], s[16:17] offset:1536
	s_add_i32 s27, s27, s1
	s_cmp_lt_u32 s27, 0x10000
	s_cselect_b32 s3, s27, s0
	s_sub_u32 s3, 0xffff, s3
	s_lshl_b32 s4, s3, 12
	s_add_u32 s6, s68, s4
	s_addc_u32 s7, s69, 0
	s_lshr_b32 s4, s3, 12
	s_mul_i32 s4, s4, 0x6000
	s_add_u32 s20, s88, s4
	s_addc_u32 s21, s89, 0
	s_add_u32 s22, s20, 0x101000
	s_addc_u32 s23, s21, 0
	s_add_u32 s20, s20, 0x100000
	s_addc_u32 s21, s21, 0
	global_load_dwordx4 v[122:125], v206, s[6:7]
	global_load_dwordx4 v[126:129], v206, s[6:7] offset:1024
	global_load_dwordx4 v[130:133], v206, s[6:7] offset:2048
	global_load_dwordx4 v[134:137], v206, s[6:7] offset:3072
	global_load_dwordx4 v[138:141], v206, s[22:23]
	global_load_dwordx4 v[142:145], v206, s[22:23] offset:1024
	global_load_dwordx4 v[146:149], v206, s[22:23] offset:2048
	global_load_dwordx4 v[150:153], v206, s[22:23] offset:3072
	global_load_dwordx4 v[154:157], v206, s[20:21]
	global_load_dwordx4 v[158:161], v206, s[20:21] offset:1024
	global_load_dwordx4 v[162:165], v206, s[20:21] offset:2048
	global_load_dwordx4 v[166:169], v206, s[20:21] offset:3072
	s_branch .LNc_loop
.LNc_done:
	s_waitcnt vmcnt(0)
.LBB0_395:
	s_or_b64 exec, exec, s[14:15]
.LBB0_396:
	s_andn2_saveexec_b64 s[10:11], s[10:11]
	s_cbranch_execz .LBB0_757
	v_mov_b32_e32 v1, v180
	s_mov_b32 s16, 0x10000
	v_ashrrev_i32_e32 v0, 6, v1
	v_add_u32_e32 v80, s70, v0
	v_cmp_gt_i32_e32 vcc, s16, v80
	s_and_saveexec_b64 s[14:15], vcc
	s_cbranch_execz .LBB0_406
	v_mov_b32_e32 v201, 0xf800000
	v_lshrrev_b32_e32 v206, 6, v180
	v_and_b32_e32 v207, 63, v180
	v_readfirstlane_b32 s0, v206
	v_lshlrev_b32_e32 v206, 4, v207
	v_lshlrev_b32_e32 v207, 3, v207
	v_mov_b32_e32 v199, 0x358637bd
	v_mov_b32_e32 v200, 0x260
	s_lshl_b32 s1, s24, 3
	s_add_i32 s0, s0, s1
	s_lshl_b32 s2, s28, 3
	s_mul_i32 s1, s2, 3
	s_mov_b32 s19, s0
	s_add_i32 s26, s0, s2
	s_add_i32 s17, s26, s2
	s_cmp_lt_u32 s0, 0x10000
	s_cbranch_scc0 .LNd_done
	s_cmp_lt_u32 s19, 0x10000
	s_cselect_b32 s3, s19, s0
	s_sub_u32 s3, 0xffff, s3
	s_lshl_b32 s4, s3, 12
	s_add_u32 s6, s68, s4
	s_addc_u32 s7, s69, 0
	s_lshr_b32 s4, s3, 12
	s_mul_i32 s4, s4, 0x6000
	s_add_u32 s20, s88, s4
	s_addc_u32 s21, s89, 0
	s_add_u32 s22, s20, 0x101000
	s_addc_u32 s23, s21, 0
	s_add_u32 s20, s20, 0x100000
	s_addc_u32 s21, s21, 0
	global_load_dwordx4 v[0:3], v206, s[6:7]
	global_load_dwordx4 v[4:7], v206, s[6:7] offset:1024
	global_load_dwordx4 v[8:11], v206, s[6:7] offset:2048
	global_load_dwordx4 v[12:15], v206, s[6:7] offset:3072
	global_load_dwordx4 v[16:19], v206, s[22:23]
	global_load_dwordx4 v[20:23], v206, s[22:23] offset:1024
	global_load_dwordx4 v[24:27], v206, s[22:23] offset:2048
	global_load_dwordx4 v[28:31], v206, s[22:23] offset:3072
	global_load_dwordx4 v[32:35], v206, s[20:21]
	global_load_dwordx4 v[36:39], v206, s[20:21] offset:1024
	global_load_dwordx4 v[40:43], v206, s[20:21] offset:2048
	global_load_dwordx4 v[44:47], v206, s[20:21] offset:3072
	s_cmp_lt_u32 s26, 0x10000
	s_cselect_b32 s3, s26, s0
	s_sub_u32 s3, 0xffff, s3
	s_lshl_b32 s4, s3, 12
	s_add_u32 s6, s68, s4
	s_addc_u32 s7, s69, 0
	s_lshr_b32 s4, s3, 12
	s_mul_i32 s4, s4, 0x6000
	s_add_u32 s20, s88, s4
	s_addc_u32 s21, s89, 0
	s_add_u32 s22, s20, 0x101000
	s_addc_u32 s23, s21, 0
	s_add_u32 s20, s20, 0x100000
	s_addc_u32 s21, s21, 0
	global_load_dwordx4 v[48:51], v206, s[6:7]
	global_load_dwordx4 v[52:55], v206, s[6:7] offset:1024
	global_load_dwordx4 v[56:59], v206, s[6:7] offset:2048
	global_load_dwordx4 v[60:63], v206, s[6:7] offset:3072
	global_load_dwordx4 v[64:67], v206, s[22:23]
	global_load_dwordx4 v[68:71], v206, s[22:23] offset:1024
	global_load_dwordx4 v[72:75], v206, s[22:23] offset:2048
	global_load_dwordx4 v[76:79], v206, s[22:23] offset:3072
	global_load_dwordx4 v[80:83], v206, s[20:21]
	global_load_dwordx4 v[84:87], v206, s[20:21] offset:1024
	global_load_dwordx4 v[88:91], v206, s[20:21] offset:2048
	global_load_dwordx4 v[92:95], v206, s[20:21] offset:3072
	s_cmp_lt_u32 s17, 0x10000
	s_cselect_b32 s3, s17, s0
	s_sub_u32 s3, 0xffff, s3
	s_lshl_b32 s4, s3, 12
	s_add_u32 s6, s68, s4
	s_addc_u32 s7, s69, 0
	s_lshr_b32 s4, s3, 12
	s_mul_i32 s4, s4, 0x6000
	s_add_u32 s20, s88, s4
	s_addc_u32 s21, s89, 0
	s_add_u32 s22, s20, 0x101000
	s_addc_u32 s23, s21, 0
	s_add_u32 s20, s20, 0x100000
	s_addc_u32 s21, s21, 0
	global_load_dwordx4 v[122:125], v206, s[6:7]
	global_load_dwordx4 v[126:129], v206, s[6:7] offset:1024
	global_load_dwordx4 v[130:133], v206, s[6:7] offset:2048
	global_load_dwordx4 v[134:137], v206, s[6:7] offset:3072
	global_load_dwordx4 v[138:141], v206, s[22:23]
	global_load_dwordx4 v[142:145], v206, s[22:23] offset:1024
	global_load_dwordx4 v[146:149], v206, s[22:23] offset:2048
	global_load_dwordx4 v[150:153], v206, s[22:23] offset:3072
	global_load_dwordx4 v[154:157], v206, s[20:21]
	global_load_dwordx4 v[158:161], v206, s[20:21] offset:1024
	global_load_dwordx4 v[162:165], v206, s[20:21] offset:2048
	global_load_dwordx4 v[166:169], v206, s[20:21] offset:3072
; __device__ __forceinline__ unsigned cvt_pk_bf16(float lo, float hi) { unsigned r; asm volatile("v_cvt_pk_bf16_f32 %0, %1, %2" : "=v"(r) : "v"(lo), "v"(hi)); return r; }
; __device__ __forceinline__ void phase_norm_mod(const float* x, const float* mod_shift, const float* mod_scale, bf16_t* H, int) {
;     ...
;         for (int r = 0; r < NR; ++r) { const int m = M - 1 - (m0 + r * NGW < M ? m0 + r * NGW : m0); const f32x4* xr = (const f32x4*)(x + (size_t)m * D) + lane;
; #pragma unroll
;             for (int j = 0; j < 4; ++j) v[r][j] = xr[64 * j]; }
; #pragma unroll
;         for (int r = 0; r < NR; ++r) { const int m = M - 1 - (m0 + r * NGW); if (m >= 0) {
;             const int b = m >> 12; float s = 0.f;
; #pragma unroll
;             for (int j = 0; j < 4; ++j) s += (v[r][j].x * v[r][j].x + v[r][j].y * v[r][j].y) + (v[r][j].z * v[r][j].z + v[r][j].w * v[r][j].w);
;             const float rstd = 1.0f / sqrtf(wave_sum(s) * (1.f / D) + 1e-6f);
;             const f32x4* sh = (const f32x4*)(mod_shift + (size_t)b * 6144) + lane;
;             const f32x4* sc = (const f32x4*)(mod_scale + (size_t)b * 6144) + lane;
;             u32x2* o = (u32x2*)(H + (size_t)m * D) + lane;
; #pragma unroll
;             for (int j = 0; j < 4; ++j) { const f32x4 a = sh[64 * j], c = sc[64 * j]; const f32x4 h = v[r][j] * rstd * (c + 1.0f) + a;
;                 u32x2 w; w.x = cvt_pk_bf16(h.x, h.y); w.y = cvt_pk_bf16(h.z, h.w); o[64 * j] = w; } } }
.LNd_loop:
	s_cmp_lt_u32 s19, 0x10000
	s_cbranch_scc0 .LNd_done
	s_waitcnt vmcnt(24)
	v_pk_mul_f32 v[202:203], v[0:1], v[0:1]
	v_pk_mul_f32 v[204:205], v[2:3], v[2:3]
	v_pk_fma_f32 v[202:203], v[4:5], v[4:5], v[202:203]
	v_pk_fma_f32 v[204:205], v[6:7], v[6:7], v[204:205]
	v_pk_fma_f32 v[202:203], v[8:9], v[8:9], v[202:203]
	v_pk_fma_f32 v[204:205], v[10:11], v[10:11], v[204:205]
	v_pk_fma_f32 v[202:203], v[12:13], v[12:13], v[202:203]
	v_pk_fma_f32 v[204:205], v[14:15], v[14:15], v[204:205]
	v_pk_add_f32 v[202:203], v[202:203], v[204:205]
	s_sub_u32 s3, 0xffff, s19
	s_lshl_b32 s4, s3, 11
	v_add_f32_e32 v190, v202, v203
	s_add_u32 s12, s88, s4
	s_addc_u32 s13, s89, 0
	s_nop 1
	v_add_f32_dpp v190, v190, v190 quad_perm:[1,0,3,2] row_mask:0xf bank_mask:0xf bound_ctrl:1
	s_nop 1
	v_add_f32_dpp v190, v190, v190 quad_perm:[2,3,0,1] row_mask:0xf bank_mask:0xf bound_ctrl:1
	s_nop 1
	v_add_f32_dpp v190, v190, v190 row_half_mirror row_mask:0xf bank_mask:0xf bound_ctrl:1
	s_nop 1
	v_add_f32_dpp v190, v190, v190 row_mirror row_mask:0xf bank_mask:0xf bound_ctrl:1
	s_add_u32 s12, s12, 0x3c00000
	s_addc_u32 s13, s13, 0
	v_readlane_b32 s4, v190, 0
	v_readlane_b32 s5, v190, 16
	v_readlane_b32 s3, v190, 32
	s_nop 1
	v_mov_b32_e32 v191, s4
	v_add_f32_e32 v191, s5, v191
	v_readlane_b32 s4, v190, 48
	v_add_f32_e32 v191, s3, v191
	s_nop 1
	v_add_f32_e32 v190, s4, v191
	v_fmamk_f32 v190, v190, 0x3a800000, v199
	v_mul_f32_e32 v191, 0x4f800000, v190
	v_cmp_gt_f32_e32 vcc, v201, v190
	s_nop 1
	v_cndmask_b32_e32 v192, v190, v191, vcc
	v_sqrt_f32_e32 v194, v192
	s_nop 0
	v_add_u32_e32 v195, -1, v194
	v_add_u32_e32 v196, 1, v194
	v_fma_f32 v197, -v195, v194, v192
	v_fma_f32 v198, -v196, v194, v192
	v_cmp_ge_f32_e64 s[4:5], 0, v197
	s_nop 1
	v_cndmask_b32_e64 v194, v194, v195, s[4:5]
	v_cmp_lt_f32_e64 s[4:5], 0, v198
	s_nop 1
	v_cndmask_b32_e64 v194, v194, v196, s[4:5]
	v_mul_f32_e32 v195, 0x37800000, v194
	v_cndmask_b32_e32 v194, v194, v195, vcc
	v_cmp_class_f32_e32 vcc, v192, v200
	s_nop 1
	v_cndmask_b32_e32 v192, v194, v192, vcc
	v_div_scale_f32 v194, s[4:5], v192, v192, 1.0
	v_rcp_f32_e32 v195, v194
	v_div_scale_f32 v196, vcc, 1.0, v192, 1.0
	v_fma_f32 v197, -v194, v195, 1.0
	v_fmac_f32_e32 v195, v197, v195
	v_mul_f32_e32 v197, v196, v195
	v_fma_f32 v198, -v194, v197, v196
	v_fmac_f32_e32 v197, v198, v195
	v_fma_f32 v194, -v194, v197, v196
	v_div_fmas_f32 v194, v194, v195, v197
	v_div_fixup_f32 v192, v194, v192, 1.0
	v_pk_mul_f32 v[0:1], v[0:1], v[192:193] op_sel_hi:[1,0]
	v_pk_mul_f32 v[2:3], v[2:3], v[192:193] op_sel_hi:[1,0]
	v_pk_add_f32 v[16:17], v[16:17], 1.0 op_sel_hi:[1,0]
	v_pk_add_f32 v[18:19], v[18:19], 1.0 op_sel_hi:[1,0]
	v_pk_fma_f32 v[0:1], v[16:17], v[0:1], v[32:33]
	v_pk_fma_f32 v[2:3], v[18:19], v[2:3], v[34:35]
	v_cvt_pk_bf16_f32 v182, v0, v1
	v_cvt_pk_bf16_f32 v183, v2, v3
	v_pk_mul_f32 v[4:5], v[4:5], v[192:193] op_sel_hi:[1,0]
	v_pk_mul_f32 v[6:7], v[6:7], v[192:193] op_sel_hi:[1,0]
	v_pk_add_f32 v[20:21], v[20:21], 1.0 op_sel_hi:[1,0]
	v_pk_add_f32 v[22:23], v[22:23], 1.0 op_sel_hi:[1,0]
	v_pk_fma_f32 v[4:5], v[20:21], v[4:5], v[36:37]
	v_pk_fma_f32 v[6:7], v[22:23], v[6:7], v[38:39]
	v_cvt_pk_bf16_f32 v184, v4, v5
	v_cvt_pk_bf16_f32 v185, v6, v7
	v_pk_mul_f32 v[8:9], v[8:9], v[192:193] op_sel_hi:[1,0]
	v_pk_mul_f32 v[10:11], v[10:11], v[192:193] op_sel_hi:[1,0]
	v_pk_add_f32 v[24:25], v[24:25], 1.0 op_sel_hi:[1,0]
	v_pk_add_f32 v[26:27], v[26:27], 1.0 op_sel_hi:[1,0]
	v_pk_fma_f32 v[8:9], v[24:25], v[8:9], v[40:41]
	v_pk_fma_f32 v[10:11], v[26:27], v[10:11], v[42:43]
	v_cvt_pk_bf16_f32 v186, v8, v9
	v_cvt_pk_bf16_f32 v187, v10, v11
	v_pk_mul_f32 v[12:13], v[12:13], v[192:193] op_sel_hi:[1,0]
	v_pk_mul_f32 v[14:15], v[14:15], v[192:193] op_sel_hi:[1,0]
	v_pk_add_f32 v[28:29], v[28:29], 1.0 op_sel_hi:[1,0]
	v_pk_add_f32 v[30:31], v[30:31], 1.0 op_sel_hi:[1,0]
	v_pk_fma_f32 v[12:13], v[28:29], v[12:13], v[44:45]
	v_pk_fma_f32 v[14:15], v[30:31], v[14:15], v[46:47]
	v_cvt_pk_bf16_f32 v188, v12, v13
	v_cvt_pk_bf16_f32 v189, v14, v15
	global_store_dwordx2 v207, v[182:183], s[12:13]
	global_store_dwordx2 v207, v[184:185], s[12:13] offset:512
	global_store_dwordx2 v207, v[186:187], s[12:13] offset:1024
	global_store_dwordx2 v207, v[188:189], s[12:13] offset:1536
	s_add_i32 s19, s19, s1
	s_cmp_lt_u32 s19, 0x10000
	s_cselect_b32 s3, s19, s0
	s_sub_u32 s3, 0xffff, s3
	s_lshl_b32 s4, s3, 12
	s_add_u32 s6, s68, s4
	s_addc_u32 s7, s69, 0
	s_lshr_b32 s4, s3, 12
	s_mul_i32 s4, s4, 0x6000
	s_add_u32 s20, s88, s4
	s_addc_u32 s21, s89, 0
	s_add_u32 s22, s20, 0x101000
	s_addc_u32 s23, s21, 0
	s_add_u32 s20, s20, 0x100000
	s_addc_u32 s21, s21, 0
	global_load_dwordx4 v[0:3], v206, s[6:7]
	global_load_dwordx4 v[4:7], v206, s[6:7] offset:1024
	global_load_dwordx4 v[8:11], v206, s[6:7] offset:2048
	global_load_dwordx4 v[12:15], v206, s[6:7] offset:3072
	global_load_dwordx4 v[16:19], v206, s[22:23]
	global_load_dwordx4 v[20:23], v206, s[22:23] offset:1024
	global_load_dwordx4 v[24:27], v206, s[22:23] offset:2048
	global_load_dwordx4 v[28:31], v206, s[22:23] offset:3072
	global_load_dwordx4 v[32:35], v206, s[20:21]
	global_load_dwordx4 v[36:39], v206, s[20:21] offset:1024
	global_load_dwordx4 v[40:43], v206, s[20:21] offset:2048
	global_load_dwordx4 v[44:47], v206, s[20:21] offset:3072
	s_cmp_lt_u32 s26, 0x10000
	s_cbranch_scc0 .LNd_done
; __device__ __forceinline__ unsigned cvt_pk_bf16(float lo, float hi) { unsigned r; asm volatile("v_cvt_pk_bf16_f32 %0, %1, %2" : "=v"(r) : "v"(lo), "v"(hi)); return r; }
; __device__ __forceinline__ void phase_norm_mod(const float* x, const float* mod_shift, const float* mod_scale, bf16_t* H, int) {
;     ...
;         for (int r = 0; r < NR; ++r) { const int m = M - 1 - (m0 + r * NGW < M ? m0 + r * NGW : m0); const f32x4* xr = (const f32x4*)(x + (size_t)m * D) + lane;
; #pragma unroll
;             for (int j = 0; j < 4; ++j) v[r][j] = xr[64 * j]; }
; #pragma unroll
;         for (int r = 0; r < NR; ++r) { const int m = M - 1 - (m0 + r * NGW); if (m >= 0) {
;             const int b = m >> 12; float s = 0.f;
; #pragma unroll
;             for (int j = 0; j < 4; ++j) s += (v[r][j].x * v[r][j].x + v[r][j].y * v[r][j].y) + (v[r][j].z * v[r][j].z + v[r][j].w * v[r][j].w);
;             const float rstd = 1.0f / sqrtf(wave_sum(s) * (1.f / D) + 1e-6f);
;             const f32x4* sh = (const f32x4*)(mod_shift + (size_t)b * 6144) + lane;
;             const f32x4* sc = (const f32x4*)(mod_scale + (size_t)b * 6144) + lane;
;             u32x2* o = (u32x2*)(H + (size_t)m * D) + lane;
; #pragma unroll
;             for (int j = 0; j < 4; ++j) { const f32x4 a = sh[64 * j], c = sc[64 * j]; const f32x4 h = v[r][j] * rstd * (c + 1.0f) + a;
;                 u32x2 w; w.x = cvt_pk_bf16(h.x, h.y); w.y = cvt_pk_bf16(h.z, h.w); o[64 * j] = w; } } }
	s_waitcnt vmcnt(24)
	v_pk_mul_f32 v[202:203], v[48:49], v[48:49]
	v_pk_mul_f32 v[204:205], v[50:51], v[50:51]
	v_pk_fma_f32 v[202:203], v[52:53], v[52:53], v[202:203]
	v_pk_fma_f32 v[204:205], v[54:55], v[54:55], v[204:205]
	v_pk_fma_f32 v[202:203], v[56:57], v[56:57], v[202:203]
	v_pk_fma_f32 v[204:205], v[58:59], v[58:59], v[204:205]
	v_pk_fma_f32 v[202:203], v[60:61], v[60:61], v[202:203]
	v_pk_fma_f32 v[204:205], v[62:63], v[62:63], v[204:205]
	v_pk_add_f32 v[202:203], v[202:203], v[204:205]
	s_sub_u32 s3, 0xffff, s26
	s_lshl_b32 s4, s3, 11
	v_add_f32_e32 v190, v202, v203
	s_add_u32 s12, s88, s4
	s_addc_u32 s13, s89, 0
	s_nop 1
	v_add_f32_dpp v190, v190, v190 quad_perm:[1,0,3,2] row_mask:0xf bank_mask:0xf bound_ctrl:1
	s_nop 1
	v_add_f32_dpp v190, v190, v190 quad_perm:[2,3,0,1] row_mask:0xf bank_mask:0xf bound_ctrl:1
	s_nop 1
	v_add_f32_dpp v190, v190, v190 row_half_mirror row_mask:0xf bank_mask:0xf bound_ctrl:1
	s_nop 1
	v_add_f32_dpp v190, v190, v190 row_mirror row_mask:0xf bank_mask:0xf bound_ctrl:1
	s_add_u32 s12, s12, 0x3c00000
	s_addc_u32 s13, s13, 0
	v_readlane_b32 s4, v190, 0
	v_readlane_b32 s5, v190, 16
	v_readlane_b32 s3, v190, 32
	s_nop 1
	v_mov_b32_e32 v191, s4
	v_add_f32_e32 v191, s5, v191
	v_readlane_b32 s4, v190, 48
	v_add_f32_e32 v191, s3, v191
	s_nop 1
	v_add_f32_e32 v190, s4, v191
	v_fmamk_f32 v190, v190, 0x3a800000, v199
	v_mul_f32_e32 v191, 0x4f800000, v190
	v_cmp_gt_f32_e32 vcc, v201, v190
	s_nop 1
	v_cndmask_b32_e32 v192, v190, v191, vcc
	v_sqrt_f32_e32 v194, v192
	s_nop 0
	v_add_u32_e32 v195, -1, v194
	v_add_u32_e32 v196, 1, v194
	v_fma_f32 v197, -v195, v194, v192
	v_fma_f32 v198, -v196, v194, v192
	v_cmp_ge_f32_e64 s[4:5], 0, v197
	s_nop 1
	v_cndmask_b32_e64 v194, v194, v195, s[4:5]
	v_cmp_lt_f32_e64 s[4:5], 0, v198
	s_nop 1
	v_cndmask_b32_e64 v194, v194, v196, s[4:5]
	v_mul_f32_e32 v195, 0x37800000, v194
	v_cndmask_b32_e32 v194, v194, v195, vcc
	v_cmp_class_f32_e32 vcc, v192, v200
	s_nop 1
	v_cndmask_b32_e32 v192, v194, v192, vcc
	v_div_scale_f32 v194, s[4:5], v192, v192, 1.0
	v_rcp_f32_e32 v195, v194
	v_div_scale_f32 v196, vcc, 1.0, v192, 1.0
	v_fma_f32 v197, -v194, v195, 1.0
	v_fmac_f32_e32 v195, v197, v195
	v_mul_f32_e32 v197, v196, v195
	v_fma_f32 v198, -v194, v197, v196
	v_fmac_f32_e32 v197, v198, v195
	v_fma_f32 v194, -v194, v197, v196
	v_div_fmas_f32 v194, v194, v195, v197
	v_div_fixup_f32 v192, v194, v192, 1.0
	v_pk_mul_f32 v[48:49], v[48:49], v[192:193] op_sel_hi:[1,0]
	v_pk_mul_f32 v[50:51], v[50:51], v[192:193] op_sel_hi:[1,0]
	v_pk_add_f32 v[64:65], v[64:65], 1.0 op_sel_hi:[1,0]
	v_pk_add_f32 v[66:67], v[66:67], 1.0 op_sel_hi:[1,0]
	v_pk_fma_f32 v[48:49], v[64:65], v[48:49], v[80:81]
	v_pk_fma_f32 v[50:51], v[66:67], v[50:51], v[82:83]
	v_cvt_pk_bf16_f32 v182, v48, v49
	v_cvt_pk_bf16_f32 v183, v50, v51
	v_pk_mul_f32 v[52:53], v[52:53], v[192:193] op_sel_hi:[1,0]
	v_pk_mul_f32 v[54:55], v[54:55], v[192:193] op_sel_hi:[1,0]
	v_pk_add_f32 v[68:69], v[68:69], 1.0 op_sel_hi:[1,0]
	v_pk_add_f32 v[70:71], v[70:71], 1.0 op_sel_hi:[1,0]
	v_pk_fma_f32 v[52:53], v[68:69], v[52:53], v[84:85]
	v_pk_fma_f32 v[54:55], v[70:71], v[54:55], v[86:87]
	v_cvt_pk_bf16_f32 v184, v52, v53
	v_cvt_pk_bf16_f32 v185, v54, v55
	v_pk_mul_f32 v[56:57], v[56:57], v[192:193] op_sel_hi:[1,0]
	v_pk_mul_f32 v[58:59], v[58:59], v[192:193] op_sel_hi:[1,0]
	v_pk_add_f32 v[72:73], v[72:73], 1.0 op_sel_hi:[1,0]
	v_pk_add_f32 v[74:75], v[74:75], 1.0 op_sel_hi:[1,0]
	v_pk_fma_f32 v[56:57], v[72:73], v[56:57], v[88:89]
	v_pk_fma_f32 v[58:59], v[74:75], v[58:59], v[90:91]
	v_cvt_pk_bf16_f32 v186, v56, v57
	v_cvt_pk_bf16_f32 v187, v58, v59
	v_pk_mul_f32 v[60:61], v[60:61], v[192:193] op_sel_hi:[1,0]
	v_pk_mul_f32 v[62:63], v[62:63], v[192:193] op_sel_hi:[1,0]
	v_pk_add_f32 v[76:77], v[76:77], 1.0 op_sel_hi:[1,0]
	v_pk_add_f32 v[78:79], v[78:79], 1.0 op_sel_hi:[1,0]
	v_pk_fma_f32 v[60:61], v[76:77], v[60:61], v[92:93]
	v_pk_fma_f32 v[62:63], v[78:79], v[62:63], v[94:95]
	v_cvt_pk_bf16_f32 v188, v60, v61
	v_cvt_pk_bf16_f32 v189, v62, v63
	global_store_dwordx2 v207, v[182:183], s[12:13]
	global_store_dwordx2 v207, v[184:185], s[12:13] offset:512
	global_store_dwordx2 v207, v[186:187], s[12:13] offset:1024
	global_store_dwordx2 v207, v[188:189], s[12:13] offset:1536
	s_add_i32 s26, s26, s1
	s_cmp_lt_u32 s26, 0x10000
	s_cselect_b32 s3, s26, s0
	s_sub_u32 s3, 0xffff, s3
	s_lshl_b32 s4, s3, 12
	s_add_u32 s6, s68, s4
	s_addc_u32 s7, s69, 0
	s_lshr_b32 s4, s3, 12
	s_mul_i32 s4, s4, 0x6000
	s_add_u32 s20, s88, s4
	s_addc_u32 s21, s89, 0
	s_add_u32 s22, s20, 0x101000
	s_addc_u32 s23, s21, 0
	s_add_u32 s20, s20, 0x100000
	s_addc_u32 s21, s21, 0
	global_load_dwordx4 v[48:51], v206, s[6:7]
	global_load_dwordx4 v[52:55], v206, s[6:7] offset:1024
	global_load_dwordx4 v[56:59], v206, s[6:7] offset:2048
	global_load_dwordx4 v[60:63], v206, s[6:7] offset:3072
	global_load_dwordx4 v[64:67], v206, s[22:23]
	global_load_dwordx4 v[68:71], v206, s[22:23] offset:1024
	global_load_dwordx4 v[72:75], v206, s[22:23] offset:2048
	global_load_dwordx4 v[76:79], v206, s[22:23] offset:3072
	global_load_dwordx4 v[80:83], v206, s[20:21]
	global_load_dwordx4 v[84:87], v206, s[20:21] offset:1024
	global_load_dwordx4 v[88:91], v206, s[20:21] offset:2048
	global_load_dwordx4 v[92:95], v206, s[20:21] offset:3072
	s_cmp_lt_u32 s17, 0x10000
	s_cbranch_scc0 .LNd_done
; __device__ __forceinline__ unsigned cvt_pk_bf16(float lo, float hi) { unsigned r; asm volatile("v_cvt_pk_bf16_f32 %0, %1, %2" : "=v"(r) : "v"(lo), "v"(hi)); return r; }
; __device__ __forceinline__ void phase_norm_mod(const float* x, const float* mod_shift, const float* mod_scale, bf16_t* H, int) {
;     ...
;         for (int r = 0; r < NR; ++r) { const int m = M - 1 - (m0 + r * NGW < M ? m0 + r * NGW : m0); const f32x4* xr = (const f32x4*)(x + (size_t)m * D) + lane;
; #pragma unroll
;             for (int j = 0; j < 4; ++j) v[r][j] = xr[64 * j]; }
; #pragma unroll
;         for (int r = 0; r < NR; ++r) { const int m = M - 1 - (m0 + r * NGW); if (m >= 0) {
;             const int b = m >> 12; float s = 0.f;
; #pragma unroll
;             for (int j = 0; j < 4; ++j) s += (v[r][j].x * v[r][j].x + v[r][j].y * v[r][j].y) + (v[r][j].z * v[r][j].z + v[r][j].w * v[r][j].w);
;             const float rstd = 1.0f / sqrtf(wave_sum(s) * (1.f / D) + 1e-6f);
;             const f32x4* sh = (const f32x4*)(mod_shift + (size_t)b * 6144) + lane;
;             const f32x4* sc = (const f32x4*)(mod_scale + (size_t)b * 6144) + lane;
;             u32x2* o = (u32x2*)(H + (size_t)m * D) + lane;
; #pragma unroll
;             for (int j = 0; j < 4; ++j) { const f32x4 a = sh[64 * j], c = sc[64 * j]; const f32x4 h = v[r][j] * rstd * (c + 1.0f) + a;
;                 u32x2 w; w.x = cvt_pk_bf16(h.x, h.y); w.y = cvt_pk_bf16(h.z, h.w); o[64 * j] = w; } } }
	s_waitcnt vmcnt(24)
	v_pk_mul_f32 v[202:203], v[122:123], v[122:123]
	v_pk_mul_f32 v[204:205], v[124:125], v[124:125]
	v_pk_fma_f32 v[202:203], v[126:127], v[126:127], v[202:203]
	v_pk_fma_f32 v[204:205], v[128:129], v[128:129], v[204:205]
	v_pk_fma_f32 v[202:203], v[130:131], v[130:131], v[202:203]
	v_pk_fma_f32 v[204:205], v[132:133], v[132:133], v[204:205]
	v_pk_fma_f32 v[202:203], v[134:135], v[134:135], v[202:203]
	v_pk_fma_f32 v[204:205], v[136:137], v[136:137], v[204:205]
	v_pk_add_f32 v[202:203], v[202:203], v[204:205]
	s_sub_u32 s3, 0xffff, s17
	s_lshl_b32 s4, s3, 11
	v_add_f32_e32 v190, v202, v203
	s_add_u32 s12, s88, s4
	s_addc_u32 s13, s89, 0
	s_nop 1
	v_add_f32_dpp v190, v190, v190 quad_perm:[1,0,3,2] row_mask:0xf bank_mask:0xf bound_ctrl:1
	s_nop 1
	v_add_f32_dpp v190, v190, v190 quad_perm:[2,3,0,1] row_mask:0xf bank_mask:0xf bound_ctrl:1
	s_nop 1
	v_add_f32_dpp v190, v190, v190 row_half_mirror row_mask:0xf bank_mask:0xf bound_ctrl:1
	s_nop 1
	v_add_f32_dpp v190, v190, v190 row_mirror row_mask:0xf bank_mask:0xf bound_ctrl:1
	s_add_u32 s12, s12, 0x3c00000
	s_addc_u32 s13, s13, 0
	v_readlane_b32 s4, v190, 0
	v_readlane_b32 s5, v190, 16
	v_readlane_b32 s3, v190, 32
	s_nop 1
	v_mov_b32_e32 v191, s4
	v_add_f32_e32 v191, s5, v191
	v_readlane_b32 s4, v190, 48
	v_add_f32_e32 v191, s3, v191
	s_nop 1
	v_add_f32_e32 v190, s4, v191
	v_fmamk_f32 v190, v190, 0x3a800000, v199
	v_mul_f32_e32 v191, 0x4f800000, v190
	v_cmp_gt_f32_e32 vcc, v201, v190
	s_nop 1
	v_cndmask_b32_e32 v192, v190, v191, vcc
	v_sqrt_f32_e32 v194, v192
	s_nop 0
	v_add_u32_e32 v195, -1, v194
	v_add_u32_e32 v196, 1, v194
	v_fma_f32 v197, -v195, v194, v192
	v_fma_f32 v198, -v196, v194, v192
	v_cmp_ge_f32_e64 s[4:5], 0, v197
	s_nop 1
	v_cndmask_b32_e64 v194, v194, v195, s[4:5]
	v_cmp_lt_f32_e64 s[4:5], 0, v198
	s_nop 1
	v_cndmask_b32_e64 v194, v194, v196, s[4:5]
	v_mul_f32_e32 v195, 0x37800000, v194
	v_cndmask_b32_e32 v194, v194, v195, vcc
	v_cmp_class_f32_e32 vcc, v192, v200
	s_nop 1
	v_cndmask_b32_e32 v192, v194, v192, vcc
	v_div_scale_f32 v194, s[4:5], v192, v192, 1.0
	v_rcp_f32_e32 v195, v194
	v_div_scale_f32 v196, vcc, 1.0, v192, 1.0
	v_fma_f32 v197, -v194, v195, 1.0
	v_fmac_f32_e32 v195, v197, v195
	v_mul_f32_e32 v197, v196, v195
	v_fma_f32 v198, -v194, v197, v196
	v_fmac_f32_e32 v197, v198, v195
	v_fma_f32 v194, -v194, v197, v196
	v_div_fmas_f32 v194, v194, v195, v197
	v_div_fixup_f32 v192, v194, v192, 1.0
	v_pk_mul_f32 v[122:123], v[122:123], v[192:193] op_sel_hi:[1,0]
	v_pk_mul_f32 v[124:125], v[124:125], v[192:193] op_sel_hi:[1,0]
	v_pk_add_f32 v[138:139], v[138:139], 1.0 op_sel_hi:[1,0]
	v_pk_add_f32 v[140:141], v[140:141], 1.0 op_sel_hi:[1,0]
	v_pk_fma_f32 v[122:123], v[138:139], v[122:123], v[154:155]
	v_pk_fma_f32 v[124:125], v[140:141], v[124:125], v[156:157]
	v_cvt_pk_bf16_f32 v182, v122, v123
	v_cvt_pk_bf16_f32 v183, v124, v125
	v_pk_mul_f32 v[126:127], v[126:127], v[192:193] op_sel_hi:[1,0]
	v_pk_mul_f32 v[128:129], v[128:129], v[192:193] op_sel_hi:[1,0]
	v_pk_add_f32 v[142:143], v[142:143], 1.0 op_sel_hi:[1,0]
	v_pk_add_f32 v[144:145], v[144:145], 1.0 op_sel_hi:[1,0]
	v_pk_fma_f32 v[126:127], v[142:143], v[126:127], v[158:159]
	v_pk_fma_f32 v[128:129], v[144:145], v[128:129], v[160:161]
	v_cvt_pk_bf16_f32 v184, v126, v127
	v_cvt_pk_bf16_f32 v185, v128, v129
	v_pk_mul_f32 v[130:131], v[130:131], v[192:193] op_sel_hi:[1,0]
	v_pk_mul_f32 v[132:133], v[132:133], v[192:193] op_sel_hi:[1,0]
	v_pk_add_f32 v[146:147], v[146:147], 1.0 op_sel_hi:[1,0]
	v_pk_add_f32 v[148:149], v[148:149], 1.0 op_sel_hi:[1,0]
	v_pk_fma_f32 v[130:131], v[146:147], v[130:131], v[162:163]
	v_pk_fma_f32 v[132:133], v[148:149], v[132:133], v[164:165]
	v_cvt_pk_bf16_f32 v186, v130, v131
	v_cvt_pk_bf16_f32 v187, v132, v133
	v_pk_mul_f32 v[134:135], v[134:135], v[192:193] op_sel_hi:[1,0]
	v_pk_mul_f32 v[136:137], v[136:137], v[192:193] op_sel_hi:[1,0]
	v_pk_add_f32 v[150:151], v[150:151], 1.0 op_sel_hi:[1,0]
	v_pk_add_f32 v[152:153], v[152:153], 1.0 op_sel_hi:[1,0]
	v_pk_fma_f32 v[134:135], v[150:151], v[134:135], v[166:167]
	v_pk_fma_f32 v[136:137], v[152:153], v[136:137], v[168:169]
	v_cvt_pk_bf16_f32 v188, v134, v135
	v_cvt_pk_bf16_f32 v189, v136, v137
	global_store_dwordx2 v207, v[182:183], s[12:13]
	global_store_dwordx2 v207, v[184:185], s[12:13] offset:512
	global_store_dwordx2 v207, v[186:187], s[12:13] offset:1024
	global_store_dwordx2 v207, v[188:189], s[12:13] offset:1536
	s_add_i32 s17, s17, s1
	s_cmp_lt_u32 s17, 0x10000
	s_cselect_b32 s3, s17, s0
	s_sub_u32 s3, 0xffff, s3
	s_lshl_b32 s4, s3, 12
	s_add_u32 s6, s68, s4
	s_addc_u32 s7, s69, 0
	s_lshr_b32 s4, s3, 12
	s_mul_i32 s4, s4, 0x6000
	s_add_u32 s20, s88, s4
	s_addc_u32 s21, s89, 0
	s_add_u32 s22, s20, 0x101000
	s_addc_u32 s23, s21, 0
	s_add_u32 s20, s20, 0x100000
	s_addc_u32 s21, s21, 0
	global_load_dwordx4 v[122:125], v206, s[6:7]
	global_load_dwordx4 v[126:129], v206, s[6:7] offset:1024
	global_load_dwordx4 v[130:133], v206, s[6:7] offset:2048
	global_load_dwordx4 v[134:137], v206, s[6:7] offset:3072
	global_load_dwordx4 v[138:141], v206, s[22:23]
	global_load_dwordx4 v[142:145], v206, s[22:23] offset:1024
	global_load_dwordx4 v[146:149], v206, s[22:23] offset:2048
	global_load_dwordx4 v[150:153], v206, s[22:23] offset:3072
	global_load_dwordx4 v[154:157], v206, s[20:21]
	global_load_dwordx4 v[158:161], v206, s[20:21] offset:1024
	global_load_dwordx4 v[162:165], v206, s[20:21] offset:2048
	global_load_dwordx4 v[166:169], v206, s[20:21] offset:3072
	s_branch .LNd_loop
; #define LAS __attribute__((address_space(3)))
; __device__ __forceinline__ void transpose_item(const float* W, int lds_, int Ksrc, int Nsrc, bf16_t* WT, int ldd, int row_off, int col_off,
;                                                const float* mu, int mode, LAS float* scr, int kb, int nb, int lane) {
;     const int k0 = 64 * kb, n0 = 32 * nb;
; #pragma unroll 8
;     for (int i = 0; i < 32; ++i) { const int kk = 2 * i + (lane >> 5), nn = lane & 31, k = k0 + kk, n = n0 + nn;
;         float v = (k < Ksrc && n < Nsrc) ? W[(size_t)k * lds_ + n] : 0.f;
;         if (mode) { const float m = mu[k & 1023]; v *= (mode == 1) ? (1.f - m) : m; }
;         scr[kk * 33 + nn] = v; }
; __device__ __forceinline__ void phase_weights(const Args& a, LAS unsigned char* lds) {
;     ...
;         LAS float* scr = (LAS float*)(lds + wave * 16384);
;         const int gw = blockIdx.x * NWAVES + wave, NGW = gridDim.x * NWAVES;
;         const float* mu = a.in[12];
;         constexpr int TOTAL = 16 * 64 + 16 * 32 + 2 * 16 * 128 + 2 * 64 * 32 + 3 * 16 * 32 + 2 * (16 * 4 + 16 * 4 + 16 * 8) + 24 * 32 + 16 * 32;
;         for (int it = gw; it < TOTAL; it += NGW) {
;             int r = it;
.LNd_done:
	s_waitcnt vmcnt(0)
.LBB0_406:
	v_writelane_b32 v234, s10, 38
	s_nop 1
	v_writelane_b32 v234, s11, 39
	s_or_b64 exec, exec, s[14:15]
	v_mov_b32_e32 v48, v180
	s_movk_i32 s0, 0x3300
	v_ashrrev_i32_e32 v0, 6, v48
	v_add_u32_e32 v49, s70, v0
	v_cmp_gt_i32_e32 vcc, s0, v49
	s_mov_b64 s[0:1], exec
	s_mov_b64 s[8:9], s[0:1]
	s_and_b64 s[2:3], s[0:1], vcc
	s_mov_b64 exec, s[2:3]
	s_cbranch_execz .LBB0_749
	v_lshlrev_b32_e32 v4, 3, v48
	v_and_b32_e32 v4, 56, v4
	v_mul_u32_u24_e32 v8, 0x84, v4
	v_lshlrev_b32_e32 v4, 1, v4
	v_mov_b32_e32 v5, 0
	v_lshlrev_b32_e32 v3, 14, v0
	v_bfe_u32 v51, v48, 3, 3
	v_lshl_add_u64 v[30:31], s[88:89], 0, v[4:5]
	s_mov_b64 s[2:3], 0x200000
	v_add_u32_e32 v1, 0, v3
	v_lshl_add_u64 v[6:7], v[30:31], 0, s[2:3]
	v_lshlrev_b32_e32 v4, 2, v51
	s_mov_b64 s[2:3], 0x600000
	v_add3_u32 v52, v1, v8, v4
	v_lshl_add_u64 v[8:9], v[30:31], 0, s[2:3]
	s_mov_b64 s[2:3], 0x800000
	v_lshl_add_u64 v[10:11], v[30:31], 0, s[2:3]
	s_mov_b64 s[2:3], 0x1000000
	v_lshl_add_u64 v[12:13], v[30:31], 0, s[2:3]
	s_mov_b64 s[2:3], 0x1800000
	v_lshl_add_u64 v[14:15], v[30:31], 0, s[2:3]
	s_mov_b64 s[2:3], 0x2000000
	v_lshl_add_u64 v[16:17], v[30:31], 0, s[2:3]
	s_mov_b64 s[2:3], 0x2800000
	v_lshl_add_u64 v[18:19], v[30:31], 0, s[2:3]
	s_add_u32 s2, s44, 0x1000
	s_mov_b64 s[4:5], 0x2e00000
	s_addc_u32 s3, s45, 0
	v_lshl_add_u64 v[20:21], v[30:31], 0, s[4:5]
	s_mov_b64 s[4:5], 0x2e00800
	v_lshl_add_u64 v[22:23], v[30:31], 0, s[4:5]
	s_add_u32 s4, s44, 0x4000
	s_mov_b64 s[12:13], 0x3000000
	s_addc_u32 s5, s45, 0
	v_lshl_add_u64 v[24:25], v[30:31], 0, s[12:13]
	s_mov_b64 s[12:13], 0x3000100
	s_add_u32 s6, s44, 0x5000
	v_lshl_add_u64 v[26:27], v[30:31], 0, s[12:13]
	s_mov_b64 s[12:13], 0x3000200
	s_addc_u32 s7, s45, 0
	v_lshl_add_u64 v[28:29], v[30:31], 0, s[12:13]
	s_mov_b64 s[12:13], 0x3300000
	v_lshl_add_u64 v[30:31], v[30:31], 0, s[12:13]
	s_add_u32 s12, s76, 0x1000000
	s_addc_u32 s13, s77, 0
	v_bfe_u32 v0, v48, 5, 1
	s_add_u32 s14, s78, 0x1000000
	v_and_b32_e32 v50, 31, v48
	s_addc_u32 s15, s79, 0
	v_mul_u32_u24_e32 v4, 0x84, v0
	v_lshlrev_b32_e32 v32, 2, v50
	s_add_u32 s16, s46, 0x1000
	v_or_b32_e32 v3, v3, v4
	s_addc_u32 s17, s47, 0
	v_add3_u32 v56, v3, v32, 0
	v_mul_u32_u24_e32 v3, 0xa0, v0
	s_add_u32 s18, s46, 0x2000
	v_lshl_or_b32 v57, v0, 6, v50
	v_or_b32_e32 v65, v3, v50
	v_lshl_or_b32 v73, v0, 10, v50
	v_add_u32_e32 v2, v1, v32
	s_movk_i32 s64, 0x84
	v_or_b32_e32 v53, 8, v51
	v_or_b32_e32 v54, 16, v51
	v_or_b32_e32 v55, 24, v51
	s_addc_u32 s19, s47, 0
	v_mov_b32_e32 v1, v0
	v_or_b32_e32 v58, 0x380, v57
	v_or_b32_e32 v59, 0x300, v57
	v_or_b32_e32 v60, 0x280, v57
	v_or_b32_e32 v61, 0x200, v57
	v_or_b32_e32 v62, 0x180, v57
	v_or_b32_e32 v63, 0x100, v57
	v_or_b32_e32 v64, 0x80, v57
	s_movk_i32 s65, 0xa0
	v_add_u32_e32 v66, 0x8c0, v65
	v_add_u32_e32 v67, 0x780, v65
	v_add_u32_e32 v68, 0x640, v65
	v_or_b32_e32 v69, 0x500, v65
	v_add_u32_e32 v70, 0x3c0, v65
	v_add_u32_e32 v71, 0x280, v65
	v_add_u32_e32 v72, 0x140, v65
	v_or_b32_e32 v74, 0x3800, v73
	v_or_b32_e32 v75, 0x3000, v73
	s_movk_i32 s70, 0x2800
	v_or_b32_e32 v76, 0x2800, v73
	v_or_b32_e32 v77, 0x2000, v73
	v_or_b32_e32 v78, 0x1800, v73
	v_or_b32_e32 v79, 0x1000, v73
	v_or_b32_e32 v80, 0x800, v73
	v_or_b32_e32 v81, 14, v0
	s_mov_b64 s[20:21], 0
	s_movk_i32 s71, 0x1ff
	s_movk_i32 s72, 0x7ff
	s_movk_i32 s73, 0xc00
	s_movk_i32 s74, 0x400
	s_movk_i32 s75, 0x7f
	v_mov_b32_e32 v82, 0x400
	s_branch .LBB0_410
